# loop-tail increments moved in front of the last barrier in 4 K loops; spurious mid-burst lgkmcnt(0) removed in the W_in loop
# baseline (speedup 1.0000x reference)
.LBB0_122:
	s_cmp_eq_u32 s89, 12
	s_cselect_b32 s42, s20, s65
	s_cselect_b32 s43, s16, s86
	s_cselect_b32 s45, s31, s88
	s_cselect_b32 s44, s59, s87
	s_add_u32 s38, s42, 0x80
	s_addc_u32 s39, s43, 0
	s_add_u32 s74, s44, 0x80
	s_addc_u32 s75, s45, 0
	s_add_i32 s35, 0, 0x10000
	s_mov_b64 s[18:19], s[68:69]
	v_add_u32_e32 v140, s35, v142
	s_add_i32 s49, 0, 0x14000
	ds_read_b128 v[136:139], v140
	ds_read_b128 v[144:147], v140 offset:1024
	ds_read_b128 v[148:151], v140 offset:2048
	ds_read_b128 v[152:155], v140 offset:3072
	v_add_u32_e32 v140, s49, v142
	ds_read_b128 v[156:159], v140
	ds_read_b128 v[160:163], v140 offset:1024
	ds_read_b128 v[164:167], v140 offset:2048
	ds_read_b128 v[168:171], v140 offset:3072
	s_mov_b32 m0, s81
	ds_read_b128 v[172:175], v143
	ds_read_b128 v[176:179], v143 offset:1024
	ds_read_b128 v[180:183], v143 offset:2048
	ds_read_b128 v[184:187], v143 offset:3072
	ds_read_b128 v[188:191], v143 offset:4096
	ds_read_b128 v[192:195], v143 offset:5120
	ds_read_b128 v[196:199], v143 offset:6144
	ds_read_b128 v[200:203], v143 offset:7168
	global_load_lds_dwordx4 v130, s[18:19]
	s_mov_b32 m0, s82
	s_nop 0
	global_load_lds_dwordx4 v132, s[18:19]
	s_add_u32 s18, s18, 0x40000
	s_addc_u32 s19, s19, 0
	s_add_i32 m0, s67, 0xc000
	s_nop 0
	global_load_lds_dwordx4 v130, s[18:19]
	s_add_i32 m0, s67, 0xe000
	s_nop 0
	global_load_lds_dwordx4 v132, s[18:19]
	s_waitcnt vmcnt(8)
	s_waitcnt lgkmcnt(0)
	s_barrier
	s_setprio 1
	s_waitcnt lgkmcnt(0)
	v_mfma_f32_16x16x32_bf16 v[126:129], v[136:139], v[172:175], v[126:129]
	v_mfma_f32_16x16x32_bf16 v[122:125], v[148:151], v[172:175], v[122:125]
	v_mfma_f32_16x16x32_bf16 v[110:113], v[136:139], v[180:183], v[110:113]
	v_mfma_f32_16x16x32_bf16 v[106:109], v[148:151], v[180:183], v[106:109]
	v_mfma_f32_16x16x32_bf16 v[92:95], v[136:139], v[188:191], v[92:95]
	v_mfma_f32_16x16x32_bf16 v[88:91], v[148:151], v[188:191], v[88:91]
	v_mfma_f32_16x16x32_bf16 v[76:79], v[136:139], v[196:199], v[76:79]
	v_mfma_f32_16x16x32_bf16 v[72:75], v[148:151], v[196:199], v[72:75]
	v_mfma_f32_16x16x32_bf16 v[126:129], v[144:147], v[176:179], v[126:129]
	v_mfma_f32_16x16x32_bf16 v[122:125], v[152:155], v[176:179], v[122:125]
	v_mfma_f32_16x16x32_bf16 v[110:113], v[144:147], v[184:187], v[110:113]
	v_mfma_f32_16x16x32_bf16 v[106:109], v[152:155], v[184:187], v[106:109]
	v_mfma_f32_16x16x32_bf16 v[92:95], v[144:147], v[192:195], v[92:95]
	v_mfma_f32_16x16x32_bf16 v[88:91], v[152:155], v[192:195], v[88:91]
	v_mfma_f32_16x16x32_bf16 v[76:79], v[144:147], v[200:203], v[76:79]
	v_mfma_f32_16x16x32_bf16 v[72:75], v[152:155], v[200:203], v[72:75]
	v_mfma_f32_16x16x32_bf16 v[118:121], v[156:159], v[172:175], v[118:121]
	v_mfma_f32_16x16x32_bf16 v[114:117], v[164:167], v[172:175], v[114:117]
	v_mfma_f32_16x16x32_bf16 v[102:105], v[156:159], v[180:183], v[102:105]
	v_mfma_f32_16x16x32_bf16 v[98:101], v[164:167], v[180:183], v[98:101]
	v_mfma_f32_16x16x32_bf16 v[84:87], v[156:159], v[188:191], v[84:87]
	v_mfma_f32_16x16x32_bf16 v[80:83], v[164:167], v[188:191], v[80:83]
	v_mfma_f32_16x16x32_bf16 v[68:71], v[156:159], v[196:199], v[68:71]
	v_mfma_f32_16x16x32_bf16 v[64:67], v[164:167], v[196:199], v[64:67]
	v_mfma_f32_16x16x32_bf16 v[118:121], v[160:163], v[176:179], v[118:121]
	v_mfma_f32_16x16x32_bf16 v[114:117], v[168:171], v[176:179], v[114:117]
	v_mfma_f32_16x16x32_bf16 v[102:105], v[160:163], v[184:187], v[102:105]
	v_mfma_f32_16x16x32_bf16 v[98:101], v[168:171], v[184:187], v[98:101]
	v_mfma_f32_16x16x32_bf16 v[84:87], v[160:163], v[192:195], v[84:87]
	v_mfma_f32_16x16x32_bf16 v[80:83], v[168:171], v[192:195], v[80:83]
	v_mfma_f32_16x16x32_bf16 v[68:71], v[160:163], v[200:203], v[68:71]
	v_mfma_f32_16x16x32_bf16 v[64:67], v[168:171], v[200:203], v[64:67]
	s_setprio 0
	s_barrier
	s_add_i32 s18, s35, s14
	s_mov_b32 m0, s18
	ds_read_b128 v[172:175], v143 offset:16384
	ds_read_b128 v[176:179], v143 offset:17408
	ds_read_b128 v[180:183], v143 offset:18432
	ds_read_b128 v[184:187], v143 offset:19456
	ds_read_b128 v[188:191], v143 offset:20480
	ds_read_b128 v[192:195], v143 offset:21504
	ds_read_b128 v[196:199], v143 offset:22528
	ds_read_b128 v[200:203], v143 offset:23552
	global_load_lds_dwordx4 v96, s[44:45]
	s_add_i32 m0, s18, 0x2000
	s_add_u32 s18, s44, 0x40000
	s_addc_u32 s19, s45, 0
	s_add_i32 s35, s49, s14
	global_load_lds_dwordx4 v134, s[44:45]
	s_mov_b32 m0, s35
	s_nop 0
	global_load_lds_dwordx4 v96, s[18:19]
	s_add_i32 m0, s35, 0x2000
	s_nop 0
	global_load_lds_dwordx4 v134, s[18:19]
	s_waitcnt vmcnt(6)
	s_waitcnt lgkmcnt(0)
	s_barrier
	s_setprio 1
	s_waitcnt lgkmcnt(0)
	v_mfma_f32_16x16x32_bf16 v[60:63], v[136:139], v[172:175], v[60:63]
	v_mfma_f32_16x16x32_bf16 v[56:59], v[148:151], v[172:175], v[56:59]
	v_mfma_f32_16x16x32_bf16 v[44:47], v[136:139], v[180:183], v[44:47]
	v_mfma_f32_16x16x32_bf16 v[40:43], v[148:151], v[180:183], v[40:43]
	v_mfma_f32_16x16x32_bf16 v[28:31], v[136:139], v[188:191], v[28:31]
	v_mfma_f32_16x16x32_bf16 v[24:27], v[148:151], v[188:191], v[24:27]
	v_mfma_f32_16x16x32_bf16 v[12:15], v[136:139], v[196:199], v[12:15]
	v_mfma_f32_16x16x32_bf16 v[8:11], v[148:151], v[196:199], v[8:11]
	v_mfma_f32_16x16x32_bf16 v[60:63], v[144:147], v[176:179], v[60:63]
	v_mfma_f32_16x16x32_bf16 v[56:59], v[152:155], v[176:179], v[56:59]
	v_mfma_f32_16x16x32_bf16 v[44:47], v[144:147], v[184:187], v[44:47]
	v_mfma_f32_16x16x32_bf16 v[40:43], v[152:155], v[184:187], v[40:43]
	v_mfma_f32_16x16x32_bf16 v[28:31], v[144:147], v[192:195], v[28:31]
	v_mfma_f32_16x16x32_bf16 v[24:27], v[152:155], v[192:195], v[24:27]
	v_mfma_f32_16x16x32_bf16 v[12:15], v[144:147], v[200:203], v[12:15]
	v_mfma_f32_16x16x32_bf16 v[8:11], v[152:155], v[200:203], v[8:11]
	v_mfma_f32_16x16x32_bf16 v[52:55], v[156:159], v[172:175], v[52:55]
	v_mfma_f32_16x16x32_bf16 v[48:51], v[164:167], v[172:175], v[48:51]
	v_mfma_f32_16x16x32_bf16 v[36:39], v[156:159], v[180:183], v[36:39]
	v_mfma_f32_16x16x32_bf16 v[32:35], v[164:167], v[180:183], v[32:35]
	v_mfma_f32_16x16x32_bf16 v[20:23], v[156:159], v[188:191], v[20:23]
	v_mfma_f32_16x16x32_bf16 v[16:19], v[164:167], v[188:191], v[16:19]
	v_mfma_f32_16x16x32_bf16 v[4:7], v[156:159], v[196:199], v[4:7]
	v_mfma_f32_16x16x32_bf16 v[0:3], v[164:167], v[196:199], v[0:3]
	v_mfma_f32_16x16x32_bf16 v[52:55], v[160:163], v[176:179], v[52:55]
	v_mfma_f32_16x16x32_bf16 v[48:51], v[168:171], v[176:179], v[48:51]
	v_mfma_f32_16x16x32_bf16 v[36:39], v[160:163], v[184:187], v[36:39]
	v_mfma_f32_16x16x32_bf16 v[32:35], v[168:171], v[184:187], v[32:35]
	v_mfma_f32_16x16x32_bf16 v[20:23], v[160:163], v[192:195], v[20:23]
	v_mfma_f32_16x16x32_bf16 v[16:19], v[168:171], v[192:195], v[16:19]
	v_mfma_f32_16x16x32_bf16 v[4:7], v[160:163], v[200:203], v[4:7]
	v_mfma_f32_16x16x32_bf16 v[0:3], v[168:171], v[200:203], v[0:3]
	s_setprio 0
	s_barrier
	s_add_i32 s35, 0, 0x18000
	v_add_u32_e32 v140, s35, v142
	s_add_i32 s44, 0, 0x1c000
	ds_read_b128 v[136:139], v140
	ds_read_b128 v[144:147], v140 offset:1024
	ds_read_b128 v[148:151], v140 offset:2048
	ds_read_b128 v[152:155], v140 offset:3072
	v_add_u32_e32 v140, s44, v142
	ds_read_b128 v[156:159], v140
	ds_read_b128 v[160:163], v140 offset:1024
	ds_read_b128 v[164:167], v140 offset:2048
	ds_read_b128 v[168:171], v140 offset:3072
	s_mov_b32 m0, s67
	s_nop 0
	global_load_lds_dwordx4 v130, s[42:43]
	s_mov_b32 m0, s73
	s_nop 0
	global_load_lds_dwordx4 v132, s[42:43]
	s_add_u32 s18, s42, 0x40000
	s_addc_u32 s19, s43, 0
	s_mov_b32 m0, s76
	ds_read_b128 v[172:175], v143 offset:32768
	ds_read_b128 v[176:179], v143 offset:33792
	ds_read_b128 v[180:183], v143 offset:34816
	ds_read_b128 v[184:187], v143 offset:35840
	ds_read_b128 v[188:191], v143 offset:36864
	ds_read_b128 v[192:195], v143 offset:37888
	ds_read_b128 v[196:199], v143 offset:38912
	ds_read_b128 v[200:203], v143 offset:39936
	global_load_lds_dwordx4 v130, s[18:19]
	s_mov_b32 m0, s77
	s_nop 0
	global_load_lds_dwordx4 v132, s[18:19]
	s_waitcnt vmcnt(8)
	s_waitcnt lgkmcnt(0)
	s_barrier
	s_setprio 1
	s_waitcnt lgkmcnt(0)
	v_mfma_f32_16x16x32_bf16 v[126:129], v[136:139], v[172:175], v[126:129]
	v_mfma_f32_16x16x32_bf16 v[122:125], v[148:151], v[172:175], v[122:125]
	v_mfma_f32_16x16x32_bf16 v[110:113], v[136:139], v[180:183], v[110:113]
	v_mfma_f32_16x16x32_bf16 v[106:109], v[148:151], v[180:183], v[106:109]
	v_mfma_f32_16x16x32_bf16 v[92:95], v[136:139], v[188:191], v[92:95]
	v_mfma_f32_16x16x32_bf16 v[88:91], v[148:151], v[188:191], v[88:91]
	v_mfma_f32_16x16x32_bf16 v[76:79], v[136:139], v[196:199], v[76:79]
	v_mfma_f32_16x16x32_bf16 v[72:75], v[148:151], v[196:199], v[72:75]
	v_mfma_f32_16x16x32_bf16 v[126:129], v[144:147], v[176:179], v[126:129]
	v_mfma_f32_16x16x32_bf16 v[122:125], v[152:155], v[176:179], v[122:125]
	v_mfma_f32_16x16x32_bf16 v[110:113], v[144:147], v[184:187], v[110:113]
	v_mfma_f32_16x16x32_bf16 v[106:109], v[152:155], v[184:187], v[106:109]
	v_mfma_f32_16x16x32_bf16 v[92:95], v[144:147], v[192:195], v[92:95]
	v_mfma_f32_16x16x32_bf16 v[88:91], v[152:155], v[192:195], v[88:91]
	v_mfma_f32_16x16x32_bf16 v[76:79], v[144:147], v[200:203], v[76:79]
	v_mfma_f32_16x16x32_bf16 v[72:75], v[152:155], v[200:203], v[72:75]
	v_mfma_f32_16x16x32_bf16 v[118:121], v[156:159], v[172:175], v[118:121]
	v_mfma_f32_16x16x32_bf16 v[114:117], v[164:167], v[172:175], v[114:117]
	v_mfma_f32_16x16x32_bf16 v[102:105], v[156:159], v[180:183], v[102:105]
	v_mfma_f32_16x16x32_bf16 v[98:101], v[164:167], v[180:183], v[98:101]
	v_mfma_f32_16x16x32_bf16 v[84:87], v[156:159], v[188:191], v[84:87]
	v_mfma_f32_16x16x32_bf16 v[80:83], v[164:167], v[188:191], v[80:83]
	v_mfma_f32_16x16x32_bf16 v[68:71], v[156:159], v[196:199], v[68:71]
	v_mfma_f32_16x16x32_bf16 v[64:67], v[164:167], v[196:199], v[64:67]
	v_mfma_f32_16x16x32_bf16 v[118:121], v[160:163], v[176:179], v[118:121]
	v_mfma_f32_16x16x32_bf16 v[114:117], v[168:171], v[176:179], v[114:117]
	v_mfma_f32_16x16x32_bf16 v[102:105], v[160:163], v[184:187], v[102:105]
	v_mfma_f32_16x16x32_bf16 v[98:101], v[168:171], v[184:187], v[98:101]
	v_mfma_f32_16x16x32_bf16 v[84:87], v[160:163], v[192:195], v[84:87]
	v_mfma_f32_16x16x32_bf16 v[80:83], v[168:171], v[192:195], v[80:83]
	v_mfma_f32_16x16x32_bf16 v[68:71], v[160:163], v[200:203], v[68:71]
	v_mfma_f32_16x16x32_bf16 v[64:67], v[168:171], v[200:203], v[64:67]
	s_setprio 0
	s_barrier
	s_add_i32 s18, s35, s14
	s_mov_b32 m0, s18
	ds_read_b128 v[172:175], v143 offset:49152
	ds_read_b128 v[176:179], v143 offset:50176
	ds_read_b128 v[180:183], v143 offset:51200
	ds_read_b128 v[184:187], v143 offset:52224
	ds_read_b128 v[188:191], v143 offset:53248
	ds_read_b128 v[192:195], v143 offset:54272
	ds_read_b128 v[196:199], v143 offset:55296
	ds_read_b128 v[200:203], v143 offset:56320
	global_load_lds_dwordx4 v96, s[74:75]
	s_add_i32 m0, s18, 0x2000
	s_add_u32 s18, s74, 0x40000
	s_addc_u32 s19, s75, 0
	s_add_i32 s35, s44, s14
	global_load_lds_dwordx4 v134, s[74:75]
	s_mov_b32 m0, s35
	s_nop 0
	global_load_lds_dwordx4 v96, s[18:19]
	s_add_i32 m0, s35, 0x2000
	s_nop 0
	global_load_lds_dwordx4 v134, s[18:19]
	s_waitcnt vmcnt(6)
	s_waitcnt lgkmcnt(0)
	s_barrier
	s_setprio 1
	s_waitcnt lgkmcnt(0)
	v_mfma_f32_16x16x32_bf16 v[60:63], v[136:139], v[172:175], v[60:63]
	v_mfma_f32_16x16x32_bf16 v[56:59], v[148:151], v[172:175], v[56:59]
	v_mfma_f32_16x16x32_bf16 v[44:47], v[136:139], v[180:183], v[44:47]
	v_mfma_f32_16x16x32_bf16 v[40:43], v[148:151], v[180:183], v[40:43]
	v_mfma_f32_16x16x32_bf16 v[28:31], v[136:139], v[188:191], v[28:31]
	v_mfma_f32_16x16x32_bf16 v[24:27], v[148:151], v[188:191], v[24:27]
	v_mfma_f32_16x16x32_bf16 v[12:15], v[136:139], v[196:199], v[12:15]
	v_mfma_f32_16x16x32_bf16 v[8:11], v[148:151], v[196:199], v[8:11]
	v_mfma_f32_16x16x32_bf16 v[60:63], v[144:147], v[176:179], v[60:63]
	v_mfma_f32_16x16x32_bf16 v[56:59], v[152:155], v[176:179], v[56:59]
	v_mfma_f32_16x16x32_bf16 v[44:47], v[144:147], v[184:187], v[44:47]
	v_mfma_f32_16x16x32_bf16 v[40:43], v[152:155], v[184:187], v[40:43]
	v_mfma_f32_16x16x32_bf16 v[28:31], v[144:147], v[192:195], v[28:31]
	v_mfma_f32_16x16x32_bf16 v[24:27], v[152:155], v[192:195], v[24:27]
	v_mfma_f32_16x16x32_bf16 v[12:15], v[144:147], v[200:203], v[12:15]
	v_mfma_f32_16x16x32_bf16 v[8:11], v[152:155], v[200:203], v[8:11]
	v_mfma_f32_16x16x32_bf16 v[52:55], v[156:159], v[172:175], v[52:55]
	v_mfma_f32_16x16x32_bf16 v[48:51], v[164:167], v[172:175], v[48:51]
	v_mfma_f32_16x16x32_bf16 v[36:39], v[156:159], v[180:183], v[36:39]
	v_mfma_f32_16x16x32_bf16 v[32:35], v[164:167], v[180:183], v[32:35]
	v_mfma_f32_16x16x32_bf16 v[20:23], v[156:159], v[188:191], v[20:23]
	v_mfma_f32_16x16x32_bf16 v[16:19], v[164:167], v[188:191], v[16:19]
	v_mfma_f32_16x16x32_bf16 v[4:7], v[156:159], v[196:199], v[4:7]
	v_mfma_f32_16x16x32_bf16 v[0:3], v[164:167], v[196:199], v[0:3]
	v_mfma_f32_16x16x32_bf16 v[52:55], v[160:163], v[176:179], v[52:55]
	v_mfma_f32_16x16x32_bf16 v[48:51], v[168:171], v[176:179], v[48:51]
	v_mfma_f32_16x16x32_bf16 v[36:39], v[160:163], v[184:187], v[36:39]
	v_mfma_f32_16x16x32_bf16 v[32:35], v[168:171], v[184:187], v[32:35]
	v_mfma_f32_16x16x32_bf16 v[20:23], v[160:163], v[192:195], v[20:23]
	v_mfma_f32_16x16x32_bf16 v[16:19], v[168:171], v[192:195], v[16:19]
	v_mfma_f32_16x16x32_bf16 v[4:7], v[160:163], v[200:203], v[4:7]
	v_mfma_f32_16x16x32_bf16 v[0:3], v[168:171], v[200:203], v[0:3]
	s_add_i32 s89, s89, 2
	s_add_u32 s65, s65, 0x100
	s_addc_u32 s86, s86, 0
	s_add_u32 s87, s87, 0x100
	s_addc_u32 s88, s88, 0
	s_add_u32 s68, s68, 0x100
	s_addc_u32 s69, s69, 0
	s_setprio 0
	s_barrier
	s_cmp_gt_u32 s89, 13
	s_cbranch_scc0 .LBB0_122
	s_and_b64 vcc, exec, s[28:29]
	s_cbranch_vccz .LBB0_125
	s_barrier

.LBB0_433:
	s_add_u32 s18, s10, 0x80
	s_addc_u32 s19, s11, 0
	s_add_u32 s10, s10, 0x100
	s_addc_u32 s11, s11, 0
	s_cmp_eq_u32 s92, 12
	s_cselect_b32 s42, s87, s10
	s_cselect_b32 s43, s9, s11
	s_cselect_b32 s45, s85, s94
	s_cselect_b32 s44, vcc_lo, vcc_hi
	s_add_u32 s38, s42, 0x80
	s_addc_u32 s39, s43, 0
	s_add_u32 s68, s44, 0x80
	s_addc_u32 s69, s45, 0
	s_add_i32 s35, 0, 0x10000
	s_add_i32 s49, 0, 0x14000
	v_add_u32_e32 v96, s35, v199
	v_add_u32_e32 v166, s49, v199
	ds_read_b128 v[138:141], v96
	ds_read_b128 v[142:145], v96 offset:1024
	ds_read_b128 v[146:149], v96 offset:2048
	ds_read_b128 v[150:153], v96 offset:3072
	ds_read_b128 v[154:157], v166
	ds_read_b128 v[158:161], v166 offset:1024
	ds_read_b128 v[162:165], v166 offset:2048
	ds_read_b128 v[166:169], v166 offset:3072
	s_mov_b32 m0, s29
	ds_read_b128 v[170:173], v200
	ds_read_b128 v[174:177], v200 offset:1024
	ds_read_b128 v[178:181], v200 offset:2048
	ds_read_b128 v[182:185], v200 offset:3072
	ds_read_b128 v[190:193], v200 offset:4096
	ds_read_b128 v[194:197], v200 offset:5120
	ds_read_b128 v[202:205], v200 offset:6144
	ds_read_b128 v[206:209], v200 offset:7168
	global_load_lds_dwordx4 v130, s[18:19]
	s_mov_b32 m0, s16
	s_nop 0
	global_load_lds_dwordx4 v134, s[18:19]
	s_add_u32 s18, s18, 0x40000
	s_addc_u32 s19, s19, 0
	s_add_i32 m0, s73, 0xc000
	s_nop 0
	global_load_lds_dwordx4 v130, s[18:19]
	s_add_i32 m0, s73, 0xe000
	s_nop 0
	global_load_lds_dwordx4 v134, s[18:19]
	s_waitcnt vmcnt(8)
	s_waitcnt lgkmcnt(0)
	s_barrier
	s_setprio 1
	s_waitcnt lgkmcnt(0)
	v_mfma_f32_16x16x32_bf16 v[126:129], v[138:141], v[170:173], v[126:129]
	v_mfma_f32_16x16x32_bf16 v[122:125], v[146:149], v[170:173], v[122:125]
	v_mfma_f32_16x16x32_bf16 v[118:121], v[138:141], v[178:181], v[118:121]
	v_mfma_f32_16x16x32_bf16 v[110:113], v[146:149], v[178:181], v[110:113]
	v_mfma_f32_16x16x32_bf16 v[102:105], v[138:141], v[190:193], v[102:105]
	v_mfma_f32_16x16x32_bf16 v[92:95], v[146:149], v[190:193], v[92:95]
	v_mfma_f32_16x16x32_bf16 v[84:87], v[138:141], v[202:205], v[84:87]
	v_mfma_f32_16x16x32_bf16 v[76:79], v[146:149], v[202:205], v[76:79]
	v_mfma_f32_16x16x32_bf16 v[126:129], v[142:145], v[174:177], v[126:129]
	v_mfma_f32_16x16x32_bf16 v[122:125], v[150:153], v[174:177], v[122:125]
	v_mfma_f32_16x16x32_bf16 v[118:121], v[142:145], v[182:185], v[118:121]
	v_mfma_f32_16x16x32_bf16 v[110:113], v[150:153], v[182:185], v[110:113]
	v_mfma_f32_16x16x32_bf16 v[102:105], v[142:145], v[194:197], v[102:105]
	v_mfma_f32_16x16x32_bf16 v[92:95], v[150:153], v[194:197], v[92:95]
	v_mfma_f32_16x16x32_bf16 v[84:87], v[142:145], v[206:209], v[84:87]
	v_mfma_f32_16x16x32_bf16 v[76:79], v[150:153], v[206:209], v[76:79]
	v_mfma_f32_16x16x32_bf16 v[114:117], v[154:157], v[170:173], v[114:117]
	v_mfma_f32_16x16x32_bf16 v[106:109], v[162:165], v[170:173], v[106:109]
	v_mfma_f32_16x16x32_bf16 v[98:101], v[154:157], v[178:181], v[98:101]
	v_mfma_f32_16x16x32_bf16 v[88:91], v[162:165], v[178:181], v[88:91]
	v_mfma_f32_16x16x32_bf16 v[80:83], v[154:157], v[190:193], v[80:83]
	v_mfma_f32_16x16x32_bf16 v[72:75], v[162:165], v[190:193], v[72:75]
	v_mfma_f32_16x16x32_bf16 v[68:71], v[154:157], v[202:205], v[68:71]
	v_mfma_f32_16x16x32_bf16 v[64:67], v[162:165], v[202:205], v[64:67]
	v_mfma_f32_16x16x32_bf16 v[114:117], v[158:161], v[174:177], v[114:117]
	v_mfma_f32_16x16x32_bf16 v[106:109], v[166:169], v[174:177], v[106:109]
	v_mfma_f32_16x16x32_bf16 v[98:101], v[158:161], v[182:185], v[98:101]
	v_mfma_f32_16x16x32_bf16 v[88:91], v[166:169], v[182:185], v[88:91]
	v_mfma_f32_16x16x32_bf16 v[80:83], v[158:161], v[194:197], v[80:83]
	v_mfma_f32_16x16x32_bf16 v[72:75], v[166:169], v[194:197], v[72:75]
	v_mfma_f32_16x16x32_bf16 v[68:71], v[158:161], v[206:209], v[68:71]
	v_mfma_f32_16x16x32_bf16 v[64:67], v[166:169], v[206:209], v[64:67]
	s_setprio 0
	s_barrier
	s_add_i32 s18, s35, s72
	s_mov_b32 m0, s18
	ds_read_b128 v[170:173], v200 offset:16384
	ds_read_b128 v[174:177], v200 offset:17408
	ds_read_b128 v[178:181], v200 offset:18432
	ds_read_b128 v[182:185], v200 offset:19456
	ds_read_b128 v[190:193], v200 offset:20480
	ds_read_b128 v[194:197], v200 offset:21504
	ds_read_b128 v[202:205], v200 offset:22528
	ds_read_b128 v[206:209], v200 offset:23552
	global_load_lds_dwordx4 v132, s[44:45]
	s_add_i32 m0, s18, 0x2000
	s_add_u32 s18, s44, 0x40000
	s_addc_u32 s19, s45, 0
	s_add_i32 s35, s49, s72
	global_load_lds_dwordx4 v136, s[44:45]
	s_mov_b32 m0, s35
	s_nop 0
	global_load_lds_dwordx4 v132, s[18:19]
	s_add_i32 m0, s35, 0x2000
	s_nop 0
	global_load_lds_dwordx4 v136, s[18:19]
	s_waitcnt vmcnt(6)
	s_waitcnt lgkmcnt(0)
	s_barrier
	s_setprio 1
	s_waitcnt lgkmcnt(0)
	v_mfma_f32_16x16x32_bf16 v[60:63], v[138:141], v[170:173], v[60:63]
	v_mfma_f32_16x16x32_bf16 v[56:59], v[146:149], v[170:173], v[56:59]
	v_mfma_f32_16x16x32_bf16 v[52:55], v[138:141], v[178:181], v[52:55]
	v_mfma_f32_16x16x32_bf16 v[44:47], v[146:149], v[178:181], v[44:47]
	v_mfma_f32_16x16x32_bf16 v[36:39], v[138:141], v[190:193], v[36:39]
	v_mfma_f32_16x16x32_bf16 v[28:31], v[146:149], v[190:193], v[28:31]
	v_mfma_f32_16x16x32_bf16 v[20:23], v[138:141], v[202:205], v[20:23]
	v_mfma_f32_16x16x32_bf16 v[12:15], v[146:149], v[202:205], v[12:15]
	v_mfma_f32_16x16x32_bf16 v[60:63], v[142:145], v[174:177], v[60:63]
	v_mfma_f32_16x16x32_bf16 v[56:59], v[150:153], v[174:177], v[56:59]
	v_mfma_f32_16x16x32_bf16 v[52:55], v[142:145], v[182:185], v[52:55]
	v_mfma_f32_16x16x32_bf16 v[44:47], v[150:153], v[182:185], v[44:47]
	v_mfma_f32_16x16x32_bf16 v[36:39], v[142:145], v[194:197], v[36:39]
	v_mfma_f32_16x16x32_bf16 v[28:31], v[150:153], v[194:197], v[28:31]
	v_mfma_f32_16x16x32_bf16 v[20:23], v[142:145], v[206:209], v[20:23]
	v_mfma_f32_16x16x32_bf16 v[12:15], v[150:153], v[206:209], v[12:15]
	v_mfma_f32_16x16x32_bf16 v[48:51], v[154:157], v[170:173], v[48:51]
	v_mfma_f32_16x16x32_bf16 v[40:43], v[162:165], v[170:173], v[40:43]
	v_mfma_f32_16x16x32_bf16 v[32:35], v[154:157], v[178:181], v[32:35]
	v_mfma_f32_16x16x32_bf16 v[24:27], v[162:165], v[178:181], v[24:27]
	v_mfma_f32_16x16x32_bf16 v[16:19], v[154:157], v[190:193], v[16:19]
	v_mfma_f32_16x16x32_bf16 v[8:11], v[162:165], v[190:193], v[8:11]
	v_mfma_f32_16x16x32_bf16 v[4:7], v[154:157], v[202:205], v[4:7]
	v_mfma_f32_16x16x32_bf16 v[0:3], v[162:165], v[202:205], v[0:3]
	v_mfma_f32_16x16x32_bf16 v[48:51], v[158:161], v[174:177], v[48:51]
	v_mfma_f32_16x16x32_bf16 v[40:43], v[166:169], v[174:177], v[40:43]
	v_mfma_f32_16x16x32_bf16 v[32:35], v[158:161], v[182:185], v[32:35]
	v_mfma_f32_16x16x32_bf16 v[24:27], v[166:169], v[182:185], v[24:27]
	v_mfma_f32_16x16x32_bf16 v[16:19], v[158:161], v[194:197], v[16:19]
	v_mfma_f32_16x16x32_bf16 v[8:11], v[166:169], v[194:197], v[8:11]
	v_mfma_f32_16x16x32_bf16 v[4:7], v[158:161], v[206:209], v[4:7]
	v_mfma_f32_16x16x32_bf16 v[0:3], v[166:169], v[206:209], v[0:3]
	s_setprio 0
	s_barrier
	s_add_i32 s35, 0, 0x18000
	v_add_u32_e32 v96, s35, v199
	s_add_i32 s44, 0, 0x1c000
	ds_read_b128 v[138:141], v96
	ds_read_b128 v[142:145], v96 offset:1024
	ds_read_b128 v[146:149], v96 offset:2048
	ds_read_b128 v[150:153], v96 offset:3072
	v_add_u32_e32 v96, s44, v199
	ds_read_b128 v[154:157], v96
	ds_read_b128 v[158:161], v96 offset:1024
	ds_read_b128 v[162:165], v96 offset:2048
	ds_read_b128 v[166:169], v96 offset:3072
	s_mov_b32 m0, s73
	s_nop 0
	global_load_lds_dwordx4 v130, s[42:43]
	s_mov_b32 m0, s74
	s_nop 0
	global_load_lds_dwordx4 v134, s[42:43]
	s_add_u32 s18, s42, 0x40000
	s_addc_u32 s19, s43, 0
	s_mov_b32 m0, s75
	ds_read_b128 v[170:173], v200 offset:32768
	ds_read_b128 v[174:177], v200 offset:33792
	ds_read_b128 v[178:181], v200 offset:34816
	ds_read_b128 v[182:185], v200 offset:35840
	ds_read_b128 v[190:193], v200 offset:36864
	ds_read_b128 v[194:197], v200 offset:37888
	ds_read_b128 v[202:205], v200 offset:38912
	ds_read_b128 v[206:209], v200 offset:39936
	global_load_lds_dwordx4 v130, s[18:19]
	s_mov_b32 m0, s83
	s_nop 0
	global_load_lds_dwordx4 v134, s[18:19]
	s_waitcnt vmcnt(8)
	s_waitcnt lgkmcnt(0)
	s_barrier
	s_setprio 1
	s_waitcnt lgkmcnt(0)
	v_mfma_f32_16x16x32_bf16 v[126:129], v[138:141], v[170:173], v[126:129]
	v_mfma_f32_16x16x32_bf16 v[122:125], v[146:149], v[170:173], v[122:125]
	v_mfma_f32_16x16x32_bf16 v[118:121], v[138:141], v[178:181], v[118:121]
	v_mfma_f32_16x16x32_bf16 v[110:113], v[146:149], v[178:181], v[110:113]
	v_mfma_f32_16x16x32_bf16 v[102:105], v[138:141], v[190:193], v[102:105]
	v_mfma_f32_16x16x32_bf16 v[92:95], v[146:149], v[190:193], v[92:95]
	v_mfma_f32_16x16x32_bf16 v[84:87], v[138:141], v[202:205], v[84:87]
	v_mfma_f32_16x16x32_bf16 v[76:79], v[146:149], v[202:205], v[76:79]
	v_mfma_f32_16x16x32_bf16 v[126:129], v[142:145], v[174:177], v[126:129]
	v_mfma_f32_16x16x32_bf16 v[122:125], v[150:153], v[174:177], v[122:125]
	v_mfma_f32_16x16x32_bf16 v[118:121], v[142:145], v[182:185], v[118:121]
	v_mfma_f32_16x16x32_bf16 v[110:113], v[150:153], v[182:185], v[110:113]
	v_mfma_f32_16x16x32_bf16 v[102:105], v[142:145], v[194:197], v[102:105]
	v_mfma_f32_16x16x32_bf16 v[92:95], v[150:153], v[194:197], v[92:95]
	v_mfma_f32_16x16x32_bf16 v[84:87], v[142:145], v[206:209], v[84:87]
	v_mfma_f32_16x16x32_bf16 v[76:79], v[150:153], v[206:209], v[76:79]
	v_mfma_f32_16x16x32_bf16 v[114:117], v[154:157], v[170:173], v[114:117]
	v_mfma_f32_16x16x32_bf16 v[106:109], v[162:165], v[170:173], v[106:109]
	v_mfma_f32_16x16x32_bf16 v[98:101], v[154:157], v[178:181], v[98:101]
	v_mfma_f32_16x16x32_bf16 v[88:91], v[162:165], v[178:181], v[88:91]
	v_mfma_f32_16x16x32_bf16 v[80:83], v[154:157], v[190:193], v[80:83]
	v_mfma_f32_16x16x32_bf16 v[72:75], v[162:165], v[190:193], v[72:75]
	v_mfma_f32_16x16x32_bf16 v[68:71], v[154:157], v[202:205], v[68:71]
	v_mfma_f32_16x16x32_bf16 v[64:67], v[162:165], v[202:205], v[64:67]
	v_mfma_f32_16x16x32_bf16 v[114:117], v[158:161], v[174:177], v[114:117]
	v_mfma_f32_16x16x32_bf16 v[106:109], v[166:169], v[174:177], v[106:109]
	v_mfma_f32_16x16x32_bf16 v[98:101], v[158:161], v[182:185], v[98:101]
	v_mfma_f32_16x16x32_bf16 v[88:91], v[166:169], v[182:185], v[88:91]
	v_mfma_f32_16x16x32_bf16 v[80:83], v[158:161], v[194:197], v[80:83]
	v_mfma_f32_16x16x32_bf16 v[72:75], v[166:169], v[194:197], v[72:75]
	v_mfma_f32_16x16x32_bf16 v[68:71], v[158:161], v[206:209], v[68:71]
	v_mfma_f32_16x16x32_bf16 v[64:67], v[166:169], v[206:209], v[64:67]
	s_setprio 0
	s_barrier
	s_add_i32 s18, s35, s72
	s_mov_b32 m0, s18
	ds_read_b128 v[170:173], v200 offset:49152
	ds_read_b128 v[174:177], v200 offset:50176
	ds_read_b128 v[178:181], v200 offset:51200
	ds_read_b128 v[182:185], v200 offset:52224
	ds_read_b128 v[190:193], v200 offset:53248
	ds_read_b128 v[194:197], v200 offset:54272
	ds_read_b128 v[202:205], v200 offset:55296
	ds_read_b128 v[206:209], v200 offset:56320
	global_load_lds_dwordx4 v132, s[68:69]
	s_add_i32 m0, s18, 0x2000
	s_add_u32 s18, s68, 0x40000
	s_addc_u32 s19, s69, 0
	s_add_i32 s35, s44, s72
	global_load_lds_dwordx4 v136, s[68:69]
	s_mov_b32 m0, s35
	s_nop 0
	global_load_lds_dwordx4 v132, s[18:19]
	s_add_i32 m0, s35, 0x2000
	s_nop 0
	global_load_lds_dwordx4 v136, s[18:19]
	s_waitcnt vmcnt(6)
	s_waitcnt lgkmcnt(0)
	s_barrier
	s_setprio 1
	s_waitcnt lgkmcnt(0)
	v_mfma_f32_16x16x32_bf16 v[60:63], v[138:141], v[170:173], v[60:63]
	v_mfma_f32_16x16x32_bf16 v[56:59], v[146:149], v[170:173], v[56:59]
	v_mfma_f32_16x16x32_bf16 v[52:55], v[138:141], v[178:181], v[52:55]
	v_mfma_f32_16x16x32_bf16 v[44:47], v[146:149], v[178:181], v[44:47]
	v_mfma_f32_16x16x32_bf16 v[36:39], v[138:141], v[190:193], v[36:39]
	v_mfma_f32_16x16x32_bf16 v[28:31], v[146:149], v[190:193], v[28:31]
	v_mfma_f32_16x16x32_bf16 v[20:23], v[138:141], v[202:205], v[20:23]
	v_mfma_f32_16x16x32_bf16 v[12:15], v[146:149], v[202:205], v[12:15]
	v_mfma_f32_16x16x32_bf16 v[60:63], v[142:145], v[174:177], v[60:63]
	v_mfma_f32_16x16x32_bf16 v[56:59], v[150:153], v[174:177], v[56:59]
	v_mfma_f32_16x16x32_bf16 v[52:55], v[142:145], v[182:185], v[52:55]
	v_mfma_f32_16x16x32_bf16 v[44:47], v[150:153], v[182:185], v[44:47]
	v_mfma_f32_16x16x32_bf16 v[36:39], v[142:145], v[194:197], v[36:39]
	v_mfma_f32_16x16x32_bf16 v[28:31], v[150:153], v[194:197], v[28:31]
	v_mfma_f32_16x16x32_bf16 v[20:23], v[142:145], v[206:209], v[20:23]
	v_mfma_f32_16x16x32_bf16 v[12:15], v[150:153], v[206:209], v[12:15]
	v_mfma_f32_16x16x32_bf16 v[48:51], v[154:157], v[170:173], v[48:51]
	v_mfma_f32_16x16x32_bf16 v[40:43], v[162:165], v[170:173], v[40:43]
	v_mfma_f32_16x16x32_bf16 v[32:35], v[154:157], v[178:181], v[32:35]
	v_mfma_f32_16x16x32_bf16 v[24:27], v[162:165], v[178:181], v[24:27]
	v_mfma_f32_16x16x32_bf16 v[16:19], v[154:157], v[190:193], v[16:19]
	v_mfma_f32_16x16x32_bf16 v[8:11], v[162:165], v[190:193], v[8:11]
	v_mfma_f32_16x16x32_bf16 v[4:7], v[154:157], v[202:205], v[4:7]
	v_mfma_f32_16x16x32_bf16 v[0:3], v[162:165], v[202:205], v[0:3]
	v_mfma_f32_16x16x32_bf16 v[48:51], v[158:161], v[174:177], v[48:51]
	v_mfma_f32_16x16x32_bf16 v[40:43], v[166:169], v[174:177], v[40:43]
	v_mfma_f32_16x16x32_bf16 v[32:35], v[158:161], v[182:185], v[32:35]
	v_mfma_f32_16x16x32_bf16 v[24:27], v[166:169], v[182:185], v[24:27]
	v_mfma_f32_16x16x32_bf16 v[16:19], v[158:161], v[194:197], v[16:19]
	v_mfma_f32_16x16x32_bf16 v[8:11], v[166:169], v[194:197], v[8:11]
	v_mfma_f32_16x16x32_bf16 v[4:7], v[158:161], v[206:209], v[4:7]
	v_mfma_f32_16x16x32_bf16 v[0:3], v[166:169], v[206:209], v[0:3]
	s_add_i32 s92, s92, 2
	s_add_u32 vcc_hi, vcc_hi, 0x100
	s_addc_u32 s94, s94, 0
	s_setprio 0
	s_barrier
	s_cmp_gt_u32 s92, 13
	s_cbranch_scc0 .LBB0_433
	s_and_b64 vcc, exec, s[76:77]
	s_cbranch_vccz .LBB0_436
	s_barrier

.LBB0_703:
	s_cmp_eq_u32 s85, 40
	s_cselect_b32 s42, s8, s81
	s_cselect_b32 s43, s9, s82
	s_cselect_b32 s45, s59, s84
	s_cselect_b32 s44, s58, s83
	s_add_u32 s38, s42, 0x80
	s_addc_u32 s39, s43, 0
	s_add_u32 s62, s44, 0x80
	s_addc_u32 s63, s45, 0
	s_add_i32 s35, 0, 0x10000
	s_mov_b64 s[18:19], s[60:61]
	v_add_u32_e32 v140, s35, v142
	s_add_i32 s49, 0, 0x14000
	ds_read_b128 v[136:139], v140
	ds_read_b128 v[144:147], v140 offset:1024
	ds_read_b128 v[148:151], v140 offset:2048
	ds_read_b128 v[152:155], v140 offset:3072
	v_add_u32_e32 v140, s49, v142
	ds_read_b128 v[156:159], v140
	ds_read_b128 v[160:163], v140 offset:1024
	ds_read_b128 v[164:167], v140 offset:2048
	ds_read_b128 v[168:171], v140 offset:3072
	s_mov_b32 m0, s74
	ds_read_b128 v[172:175], v143
	ds_read_b128 v[176:179], v143 offset:1024
	ds_read_b128 v[180:183], v143 offset:2048
	ds_read_b128 v[190:193], v143 offset:3072
	ds_read_b128 v[194:197], v143 offset:4096
	ds_read_b128 v[198:201], v143 offset:5120
	ds_read_b128 v[202:205], v143 offset:6144
	ds_read_b128 v[206:209], v143 offset:7168
	global_load_lds_dwordx4 v130, s[18:19]
	s_mov_b32 m0, s75
	s_nop 0
	global_load_lds_dwordx4 v132, s[18:19]
	s_add_u32 s18, s18, 0xb0000
	s_addc_u32 s19, s19, 0
	s_add_i32 m0, s66, 0xc000
	s_nop 0
	global_load_lds_dwordx4 v130, s[18:19]
	s_add_i32 m0, s66, 0xe000
	s_nop 0
	global_load_lds_dwordx4 v132, s[18:19]
	s_waitcnt vmcnt(8)
	s_waitcnt lgkmcnt(0)
	s_barrier
	s_setprio 1
	s_waitcnt lgkmcnt(0)
	v_mfma_f32_16x16x32_bf16 v[126:129], v[136:139], v[172:175], v[126:129]
	v_mfma_f32_16x16x32_bf16 v[122:125], v[148:151], v[172:175], v[122:125]
	v_mfma_f32_16x16x32_bf16 v[110:113], v[136:139], v[180:183], v[110:113]
	v_mfma_f32_16x16x32_bf16 v[106:109], v[148:151], v[180:183], v[106:109]
	v_mfma_f32_16x16x32_bf16 v[92:95], v[136:139], v[194:197], v[92:95]
	v_mfma_f32_16x16x32_bf16 v[88:91], v[148:151], v[194:197], v[88:91]
	v_mfma_f32_16x16x32_bf16 v[76:79], v[136:139], v[202:205], v[76:79]
	v_mfma_f32_16x16x32_bf16 v[72:75], v[148:151], v[202:205], v[72:75]
	v_mfma_f32_16x16x32_bf16 v[126:129], v[144:147], v[176:179], v[126:129]
	v_mfma_f32_16x16x32_bf16 v[122:125], v[152:155], v[176:179], v[122:125]
	v_mfma_f32_16x16x32_bf16 v[110:113], v[144:147], v[190:193], v[110:113]
	v_mfma_f32_16x16x32_bf16 v[106:109], v[152:155], v[190:193], v[106:109]
	v_mfma_f32_16x16x32_bf16 v[92:95], v[144:147], v[198:201], v[92:95]
	v_mfma_f32_16x16x32_bf16 v[88:91], v[152:155], v[198:201], v[88:91]
	v_mfma_f32_16x16x32_bf16 v[76:79], v[144:147], v[206:209], v[76:79]
	v_mfma_f32_16x16x32_bf16 v[72:75], v[152:155], v[206:209], v[72:75]
	v_mfma_f32_16x16x32_bf16 v[118:121], v[156:159], v[172:175], v[118:121]
	v_mfma_f32_16x16x32_bf16 v[114:117], v[164:167], v[172:175], v[114:117]
	v_mfma_f32_16x16x32_bf16 v[102:105], v[156:159], v[180:183], v[102:105]
	v_mfma_f32_16x16x32_bf16 v[98:101], v[164:167], v[180:183], v[98:101]
	v_mfma_f32_16x16x32_bf16 v[84:87], v[156:159], v[194:197], v[84:87]
	v_mfma_f32_16x16x32_bf16 v[80:83], v[164:167], v[194:197], v[80:83]
	v_mfma_f32_16x16x32_bf16 v[68:71], v[156:159], v[202:205], v[68:71]
	v_mfma_f32_16x16x32_bf16 v[64:67], v[164:167], v[202:205], v[64:67]
	v_mfma_f32_16x16x32_bf16 v[118:121], v[160:163], v[176:179], v[118:121]
	v_mfma_f32_16x16x32_bf16 v[114:117], v[168:171], v[176:179], v[114:117]
	v_mfma_f32_16x16x32_bf16 v[102:105], v[160:163], v[190:193], v[102:105]
	v_mfma_f32_16x16x32_bf16 v[98:101], v[168:171], v[190:193], v[98:101]
	v_mfma_f32_16x16x32_bf16 v[84:87], v[160:163], v[198:201], v[84:87]
	v_mfma_f32_16x16x32_bf16 v[80:83], v[168:171], v[198:201], v[80:83]
	v_mfma_f32_16x16x32_bf16 v[68:71], v[160:163], v[206:209], v[68:71]
	v_mfma_f32_16x16x32_bf16 v[64:67], v[168:171], v[206:209], v[64:67]
	s_setprio 0
	s_barrier
	s_add_i32 s18, s35, s14
	s_mov_b32 m0, s18
	ds_read_b128 v[172:175], v143 offset:16384
	ds_read_b128 v[176:179], v143 offset:17408
	ds_read_b128 v[180:183], v143 offset:18432
	ds_read_b128 v[190:193], v143 offset:19456
	ds_read_b128 v[194:197], v143 offset:20480
	ds_read_b128 v[198:201], v143 offset:21504
	ds_read_b128 v[202:205], v143 offset:22528
	ds_read_b128 v[206:209], v143 offset:23552
	global_load_lds_dwordx4 v96, s[44:45]
	s_add_i32 m0, s18, 0x2000
	s_add_u32 s18, s44, 0xb0000
	s_addc_u32 s19, s45, 0
	s_add_i32 s35, s49, s14
	global_load_lds_dwordx4 v134, s[44:45]
	s_mov_b32 m0, s35
	s_nop 0
	global_load_lds_dwordx4 v96, s[18:19]
	s_add_i32 m0, s35, 0x2000
	s_nop 0
	global_load_lds_dwordx4 v134, s[18:19]
	s_waitcnt vmcnt(6)
	s_waitcnt lgkmcnt(0)
	s_barrier
	s_setprio 1
	s_waitcnt lgkmcnt(0)
	v_mfma_f32_16x16x32_bf16 v[60:63], v[136:139], v[172:175], v[60:63]
	v_mfma_f32_16x16x32_bf16 v[56:59], v[148:151], v[172:175], v[56:59]
	v_mfma_f32_16x16x32_bf16 v[44:47], v[136:139], v[180:183], v[44:47]
	v_mfma_f32_16x16x32_bf16 v[40:43], v[148:151], v[180:183], v[40:43]
	v_mfma_f32_16x16x32_bf16 v[28:31], v[136:139], v[194:197], v[28:31]
	v_mfma_f32_16x16x32_bf16 v[24:27], v[148:151], v[194:197], v[24:27]
	v_mfma_f32_16x16x32_bf16 v[12:15], v[136:139], v[202:205], v[12:15]
	v_mfma_f32_16x16x32_bf16 v[8:11], v[148:151], v[202:205], v[8:11]
	v_mfma_f32_16x16x32_bf16 v[60:63], v[144:147], v[176:179], v[60:63]
	v_mfma_f32_16x16x32_bf16 v[56:59], v[152:155], v[176:179], v[56:59]
	v_mfma_f32_16x16x32_bf16 v[44:47], v[144:147], v[190:193], v[44:47]
	v_mfma_f32_16x16x32_bf16 v[40:43], v[152:155], v[190:193], v[40:43]
	v_mfma_f32_16x16x32_bf16 v[28:31], v[144:147], v[198:201], v[28:31]
	v_mfma_f32_16x16x32_bf16 v[24:27], v[152:155], v[198:201], v[24:27]
	v_mfma_f32_16x16x32_bf16 v[12:15], v[144:147], v[206:209], v[12:15]
	v_mfma_f32_16x16x32_bf16 v[8:11], v[152:155], v[206:209], v[8:11]
	v_mfma_f32_16x16x32_bf16 v[52:55], v[156:159], v[172:175], v[52:55]
	v_mfma_f32_16x16x32_bf16 v[48:51], v[164:167], v[172:175], v[48:51]
	v_mfma_f32_16x16x32_bf16 v[36:39], v[156:159], v[180:183], v[36:39]
	v_mfma_f32_16x16x32_bf16 v[32:35], v[164:167], v[180:183], v[32:35]
	v_mfma_f32_16x16x32_bf16 v[20:23], v[156:159], v[194:197], v[20:23]
	v_mfma_f32_16x16x32_bf16 v[16:19], v[164:167], v[194:197], v[16:19]
	v_mfma_f32_16x16x32_bf16 v[4:7], v[156:159], v[202:205], v[4:7]
	v_mfma_f32_16x16x32_bf16 v[0:3], v[164:167], v[202:205], v[0:3]
	v_mfma_f32_16x16x32_bf16 v[52:55], v[160:163], v[176:179], v[52:55]
	v_mfma_f32_16x16x32_bf16 v[48:51], v[168:171], v[176:179], v[48:51]
	v_mfma_f32_16x16x32_bf16 v[36:39], v[160:163], v[190:193], v[36:39]
	v_mfma_f32_16x16x32_bf16 v[32:35], v[168:171], v[190:193], v[32:35]
	v_mfma_f32_16x16x32_bf16 v[20:23], v[160:163], v[198:201], v[20:23]
	v_mfma_f32_16x16x32_bf16 v[16:19], v[168:171], v[198:201], v[16:19]
	v_mfma_f32_16x16x32_bf16 v[4:7], v[160:163], v[206:209], v[4:7]
	v_mfma_f32_16x16x32_bf16 v[0:3], v[168:171], v[206:209], v[0:3]
	s_setprio 0
	s_barrier
	s_add_i32 s35, 0, 0x18000
	v_add_u32_e32 v140, s35, v142
	s_add_i32 s44, 0, 0x1c000
	ds_read_b128 v[136:139], v140
	ds_read_b128 v[144:147], v140 offset:1024
	ds_read_b128 v[148:151], v140 offset:2048
	ds_read_b128 v[152:155], v140 offset:3072
	v_add_u32_e32 v140, s44, v142
	ds_read_b128 v[156:159], v140
	ds_read_b128 v[160:163], v140 offset:1024
	ds_read_b128 v[164:167], v140 offset:2048
	ds_read_b128 v[168:171], v140 offset:3072
	s_mov_b32 m0, s66
	s_nop 0
	global_load_lds_dwordx4 v130, s[42:43]
	s_mov_b32 m0, s67
	s_nop 0
	global_load_lds_dwordx4 v132, s[42:43]
	s_add_u32 s18, s42, 0xb0000
	s_addc_u32 s19, s43, 0
	s_mov_b32 m0, s68
	ds_read_b128 v[172:175], v143 offset:32768
	ds_read_b128 v[176:179], v143 offset:33792
	ds_read_b128 v[180:183], v143 offset:34816
	ds_read_b128 v[190:193], v143 offset:35840
	ds_read_b128 v[194:197], v143 offset:36864
	ds_read_b128 v[198:201], v143 offset:37888
	ds_read_b128 v[202:205], v143 offset:38912
	ds_read_b128 v[206:209], v143 offset:39936
	global_load_lds_dwordx4 v130, s[18:19]
	s_mov_b32 m0, s69
	s_nop 0
	global_load_lds_dwordx4 v132, s[18:19]
	s_waitcnt vmcnt(8)
	s_waitcnt lgkmcnt(0)
	s_barrier
	s_setprio 1
	s_waitcnt lgkmcnt(0)
	v_mfma_f32_16x16x32_bf16 v[126:129], v[136:139], v[172:175], v[126:129]
	v_mfma_f32_16x16x32_bf16 v[122:125], v[148:151], v[172:175], v[122:125]
	v_mfma_f32_16x16x32_bf16 v[110:113], v[136:139], v[180:183], v[110:113]
	v_mfma_f32_16x16x32_bf16 v[106:109], v[148:151], v[180:183], v[106:109]
	v_mfma_f32_16x16x32_bf16 v[92:95], v[136:139], v[194:197], v[92:95]
	v_mfma_f32_16x16x32_bf16 v[88:91], v[148:151], v[194:197], v[88:91]
	v_mfma_f32_16x16x32_bf16 v[76:79], v[136:139], v[202:205], v[76:79]
	v_mfma_f32_16x16x32_bf16 v[72:75], v[148:151], v[202:205], v[72:75]
	v_mfma_f32_16x16x32_bf16 v[126:129], v[144:147], v[176:179], v[126:129]
	v_mfma_f32_16x16x32_bf16 v[122:125], v[152:155], v[176:179], v[122:125]
	v_mfma_f32_16x16x32_bf16 v[110:113], v[144:147], v[190:193], v[110:113]
	v_mfma_f32_16x16x32_bf16 v[106:109], v[152:155], v[190:193], v[106:109]
	v_mfma_f32_16x16x32_bf16 v[92:95], v[144:147], v[198:201], v[92:95]
	v_mfma_f32_16x16x32_bf16 v[88:91], v[152:155], v[198:201], v[88:91]
	v_mfma_f32_16x16x32_bf16 v[76:79], v[144:147], v[206:209], v[76:79]
	v_mfma_f32_16x16x32_bf16 v[72:75], v[152:155], v[206:209], v[72:75]
	v_mfma_f32_16x16x32_bf16 v[118:121], v[156:159], v[172:175], v[118:121]
	v_mfma_f32_16x16x32_bf16 v[114:117], v[164:167], v[172:175], v[114:117]
	v_mfma_f32_16x16x32_bf16 v[102:105], v[156:159], v[180:183], v[102:105]
	v_mfma_f32_16x16x32_bf16 v[98:101], v[164:167], v[180:183], v[98:101]
	v_mfma_f32_16x16x32_bf16 v[84:87], v[156:159], v[194:197], v[84:87]
	v_mfma_f32_16x16x32_bf16 v[80:83], v[164:167], v[194:197], v[80:83]
	v_mfma_f32_16x16x32_bf16 v[68:71], v[156:159], v[202:205], v[68:71]
	v_mfma_f32_16x16x32_bf16 v[64:67], v[164:167], v[202:205], v[64:67]
	v_mfma_f32_16x16x32_bf16 v[118:121], v[160:163], v[176:179], v[118:121]
	v_mfma_f32_16x16x32_bf16 v[114:117], v[168:171], v[176:179], v[114:117]
	v_mfma_f32_16x16x32_bf16 v[102:105], v[160:163], v[190:193], v[102:105]
	v_mfma_f32_16x16x32_bf16 v[98:101], v[168:171], v[190:193], v[98:101]
	v_mfma_f32_16x16x32_bf16 v[84:87], v[160:163], v[198:201], v[84:87]
	v_mfma_f32_16x16x32_bf16 v[80:83], v[168:171], v[198:201], v[80:83]
	v_mfma_f32_16x16x32_bf16 v[68:71], v[160:163], v[206:209], v[68:71]
	v_mfma_f32_16x16x32_bf16 v[64:67], v[168:171], v[206:209], v[64:67]
	s_setprio 0
	s_barrier
	s_add_i32 s18, s35, s14
	s_mov_b32 m0, s18
	ds_read_b128 v[172:175], v143 offset:49152
	ds_read_b128 v[176:179], v143 offset:50176
	ds_read_b128 v[180:183], v143 offset:51200
	ds_read_b128 v[190:193], v143 offset:52224
	ds_read_b128 v[194:197], v143 offset:53248
	ds_read_b128 v[198:201], v143 offset:54272
	ds_read_b128 v[202:205], v143 offset:55296
	ds_read_b128 v[206:209], v143 offset:56320
	global_load_lds_dwordx4 v96, s[62:63]
	s_add_i32 m0, s18, 0x2000
	s_add_u32 s18, s62, 0xb0000
	s_addc_u32 s19, s63, 0
	s_add_i32 s35, s44, s14
	global_load_lds_dwordx4 v134, s[62:63]
	s_mov_b32 m0, s35
	s_nop 0
	global_load_lds_dwordx4 v96, s[18:19]
	s_add_i32 m0, s35, 0x2000
	s_nop 0
	global_load_lds_dwordx4 v134, s[18:19]
	s_waitcnt vmcnt(6)
	s_waitcnt lgkmcnt(0)
	s_barrier
	s_setprio 1
	s_waitcnt lgkmcnt(0)
	v_mfma_f32_16x16x32_bf16 v[60:63], v[136:139], v[172:175], v[60:63]
	v_mfma_f32_16x16x32_bf16 v[56:59], v[148:151], v[172:175], v[56:59]
	v_mfma_f32_16x16x32_bf16 v[44:47], v[136:139], v[180:183], v[44:47]
	v_mfma_f32_16x16x32_bf16 v[40:43], v[148:151], v[180:183], v[40:43]
	v_mfma_f32_16x16x32_bf16 v[28:31], v[136:139], v[194:197], v[28:31]
	v_mfma_f32_16x16x32_bf16 v[24:27], v[148:151], v[194:197], v[24:27]
	v_mfma_f32_16x16x32_bf16 v[12:15], v[136:139], v[202:205], v[12:15]
	v_mfma_f32_16x16x32_bf16 v[8:11], v[148:151], v[202:205], v[8:11]
	v_mfma_f32_16x16x32_bf16 v[60:63], v[144:147], v[176:179], v[60:63]
	v_mfma_f32_16x16x32_bf16 v[56:59], v[152:155], v[176:179], v[56:59]
	v_mfma_f32_16x16x32_bf16 v[44:47], v[144:147], v[190:193], v[44:47]
	v_mfma_f32_16x16x32_bf16 v[40:43], v[152:155], v[190:193], v[40:43]
	v_mfma_f32_16x16x32_bf16 v[28:31], v[144:147], v[198:201], v[28:31]
	v_mfma_f32_16x16x32_bf16 v[24:27], v[152:155], v[198:201], v[24:27]
	v_mfma_f32_16x16x32_bf16 v[12:15], v[144:147], v[206:209], v[12:15]
	v_mfma_f32_16x16x32_bf16 v[8:11], v[152:155], v[206:209], v[8:11]
	v_mfma_f32_16x16x32_bf16 v[52:55], v[156:159], v[172:175], v[52:55]
	v_mfma_f32_16x16x32_bf16 v[48:51], v[164:167], v[172:175], v[48:51]
	v_mfma_f32_16x16x32_bf16 v[36:39], v[156:159], v[180:183], v[36:39]
	v_mfma_f32_16x16x32_bf16 v[32:35], v[164:167], v[180:183], v[32:35]
	v_mfma_f32_16x16x32_bf16 v[20:23], v[156:159], v[194:197], v[20:23]
	v_mfma_f32_16x16x32_bf16 v[16:19], v[164:167], v[194:197], v[16:19]
	v_mfma_f32_16x16x32_bf16 v[4:7], v[156:159], v[202:205], v[4:7]
	v_mfma_f32_16x16x32_bf16 v[0:3], v[164:167], v[202:205], v[0:3]
	v_mfma_f32_16x16x32_bf16 v[52:55], v[160:163], v[176:179], v[52:55]
	v_mfma_f32_16x16x32_bf16 v[48:51], v[168:171], v[176:179], v[48:51]
	v_mfma_f32_16x16x32_bf16 v[36:39], v[160:163], v[190:193], v[36:39]
	v_mfma_f32_16x16x32_bf16 v[32:35], v[168:171], v[190:193], v[32:35]
	v_mfma_f32_16x16x32_bf16 v[20:23], v[160:163], v[198:201], v[20:23]
	v_mfma_f32_16x16x32_bf16 v[16:19], v[168:171], v[198:201], v[16:19]
	v_mfma_f32_16x16x32_bf16 v[4:7], v[160:163], v[206:209], v[4:7]
	v_mfma_f32_16x16x32_bf16 v[0:3], v[168:171], v[206:209], v[0:3]
	s_add_i32 s85, s85, 2
	s_add_u32 s81, s81, 0x100
	s_addc_u32 s82, s82, 0
	s_add_u32 s83, s83, 0x100
	s_addc_u32 s84, s84, 0
	s_add_u32 s60, s60, 0x100
	s_addc_u32 s61, s61, 0
	s_setprio 0
	s_barrier
	s_cmp_gt_u32 s85, 41
	s_cbranch_scc0 .LBB0_703
	s_and_b64 vcc, exec, s[30:31]
	s_cbranch_vccz .LBB0_706
	s_barrier
